# GEMM K-loops: no setprio, no duplicate wait, loop heads 64-byte aligned
# baseline (speedup 1.0000x reference)
; template <class Epi, class Sched>
; __device__ __forceinline__ void gemm_phase(PG8_LAS unsigned char* lds, const Gemm g, const Sched& S, const Epi& E) {
;     ...
;         const bool has_next = S.next(ui + 1, nxt);
;         const char* nA = has_next ? (const char*)g.A + (size_t)nxt.pm * tstep : cA; const char* nB = has_next ? (const char*)g.Bt + (size_t)nxt.pn * tstep : cB;
;         for (int t = 0; t < nt; t += 2) {
;             const bool last = (t == nt - 2);
;             const char* a1 = cA + (size_t)(t + 1) * kstep;
;             const char* a2 = last ? nA : cA + (size_t)(t + 2) * kstep; const char* b2 = last ? nB : cB + (size_t)(t + 2) * kstep;
;     ...
;         for (int a = 0; a < 2; ++a)
; #pragma unroll
;             for (int b = 0; b < 2; ++b)
; #pragma unroll
;                 for (int m = 0; m < 4; ++m)
; #pragma unroll
;                     for (int n = 0; n < 2; ++n) acc[a][b][m][n] = (f32x4){0.f, 0.f, 0.f, 0.f};
.LBB0_194:
	s_ashr_i32 s17, s16, 31
	v_cmp_lt_i64_e32 vcc, s[18:19], v[140:141]
	s_lshl_b64 s[18:19], s[16:17], 19
	s_add_u32 s18, s38, s18
	s_addc_u32 s19, s39, s19
	s_and_b64 s[24:25], vcc, exec
	s_cselect_b32 s17, s19, s29
	s_cselect_b32 s54, s18, s28
	s_ashr_i32 s15, s14, 31
	s_lshl_b64 s[24:25], s[14:15], 19
	s_add_u32 s24, s90, s24
	s_addc_u32 s25, s91, s25
	s_and_b64 s[34:35], vcc, exec
	s_cselect_b32 s15, s25, s31
	s_cselect_b32 s55, s24, s30
	s_add_u32 s28, s28, 0x40080
	s_addc_u32 s29, s29, 0
	s_add_u32 s56, s30, 0x100
	v_mov_b32_e32 v0, 0
	s_addc_u32 s57, s31, 0
	s_mov_b32 s58, -2
	v_mov_b32_e32 v1, v0
	v_mov_b32_e32 v2, v0
	v_mov_b32_e32 v3, v0
	v_mov_b32_e32 v4, v0
	v_mov_b32_e32 v5, v0
	v_mov_b32_e32 v6, v0
	v_mov_b32_e32 v7, v0
	v_mov_b32_e32 v16, v0
	v_mov_b32_e32 v17, v0
	v_mov_b32_e32 v18, v0
	v_mov_b32_e32 v19, v0
	v_mov_b32_e32 v20, v0
	v_mov_b32_e32 v21, v0
	v_mov_b32_e32 v22, v0
	v_mov_b32_e32 v23, v0
	v_mov_b32_e32 v32, v0
	v_mov_b32_e32 v33, v0
	v_mov_b32_e32 v34, v0
	v_mov_b32_e32 v35, v0
	v_mov_b32_e32 v36, v0
	v_mov_b32_e32 v37, v0
	v_mov_b32_e32 v38, v0
	v_mov_b32_e32 v39, v0
	v_mov_b32_e32 v48, v0
	v_mov_b32_e32 v49, v0
	v_mov_b32_e32 v50, v0
	v_mov_b32_e32 v51, v0
	v_mov_b32_e32 v52, v0
	v_mov_b32_e32 v53, v0
	v_mov_b32_e32 v54, v0
	v_mov_b32_e32 v55, v0
	v_mov_b32_e32 v8, v0
	v_mov_b32_e32 v9, v0
	v_mov_b32_e32 v10, v0
	v_mov_b32_e32 v11, v0
	v_mov_b32_e32 v12, v0
	v_mov_b32_e32 v13, v0
	v_mov_b32_e32 v14, v0
	v_mov_b32_e32 v15, v0
	v_mov_b32_e32 v24, v0
	v_mov_b32_e32 v25, v0
	v_mov_b32_e32 v26, v0
	v_mov_b32_e32 v27, v0
	v_mov_b32_e32 v28, v0
	v_mov_b32_e32 v29, v0
	v_mov_b32_e32 v30, v0
	v_mov_b32_e32 v31, v0
	v_mov_b32_e32 v40, v0
	v_mov_b32_e32 v41, v0
	v_mov_b32_e32 v42, v0
	v_mov_b32_e32 v43, v0
	v_mov_b32_e32 v44, v0
	v_mov_b32_e32 v45, v0
	v_mov_b32_e32 v46, v0
	v_mov_b32_e32 v47, v0
	v_mov_b32_e32 v56, v0
	v_mov_b32_e32 v57, v0
	v_mov_b32_e32 v58, v0
	v_mov_b32_e32 v59, v0
	v_mov_b32_e32 v60, v0
	v_mov_b32_e32 v61, v0
	v_mov_b32_e32 v62, v0
	v_mov_b32_e32 v63, v0
	v_mov_b32_e32 v64, v0
	v_mov_b32_e32 v65, v0
	v_mov_b32_e32 v66, v0
	v_mov_b32_e32 v67, v0
	v_mov_b32_e32 v68, v0
	v_mov_b32_e32 v69, v0
	v_mov_b32_e32 v70, v0
	v_mov_b32_e32 v71, v0
	v_mov_b32_e32 v80, v0
	v_mov_b32_e32 v81, v0
	v_mov_b32_e32 v82, v0
	v_mov_b32_e32 v83, v0
	v_mov_b32_e32 v84, v0
	v_mov_b32_e32 v85, v0
	v_mov_b32_e32 v86, v0
	v_mov_b32_e32 v87, v0
	v_mov_b32_e32 v96, v0
	v_mov_b32_e32 v97, v0
	v_mov_b32_e32 v98, v0
	v_mov_b32_e32 v99, v0
	v_mov_b32_e32 v100, v0
	v_mov_b32_e32 v101, v0
	v_mov_b32_e32 v102, v0
	v_mov_b32_e32 v103, v0
	v_mov_b32_e32 v112, v0
	v_mov_b32_e32 v113, v0
	v_mov_b32_e32 v114, v0
	v_mov_b32_e32 v115, v0
	v_mov_b32_e32 v116, v0
	v_mov_b32_e32 v117, v0
	v_mov_b32_e32 v118, v0
	v_mov_b32_e32 v119, v0
	v_mov_b32_e32 v72, v0
	v_mov_b32_e32 v73, v0
	v_mov_b32_e32 v74, v0
	v_mov_b32_e32 v75, v0
	v_mov_b32_e32 v76, v0
	v_mov_b32_e32 v77, v0
	v_mov_b32_e32 v78, v0
	v_mov_b32_e32 v79, v0
	v_mov_b32_e32 v88, v0
	v_mov_b32_e32 v89, v0
	v_mov_b32_e32 v90, v0
	v_mov_b32_e32 v91, v0
	v_mov_b32_e32 v92, v0
	v_mov_b32_e32 v93, v0
	v_mov_b32_e32 v94, v0
	v_mov_b32_e32 v95, v0
	v_mov_b32_e32 v104, v0
	v_mov_b32_e32 v105, v0
	v_mov_b32_e32 v106, v0
	v_mov_b32_e32 v107, v0
	v_mov_b32_e32 v108, v0
	v_mov_b32_e32 v109, v0
	v_mov_b32_e32 v110, v0
	v_mov_b32_e32 v111, v0
	v_mov_b32_e32 v120, v0
	v_mov_b32_e32 v121, v0
	v_mov_b32_e32 v122, v0
	v_mov_b32_e32 v123, v0
	v_mov_b32_e32 v124, v0
	v_mov_b32_e32 v125, v0
	v_mov_b32_e32 v126, v0
	v_mov_b32_e32 v127, v0
	.p2align 6

; template <class Epi, class Sched>
; __device__ __forceinline__ void gemm_phase(PG8_LAS unsigned char* lds, const Gemm g, const Sched& S, const Epi& E) {
;     ...
;         for (int t = 0; t < nt; t += 2) {
;             const bool last = (t == nt - 2);
;             const char* a1 = cA + (size_t)(t + 1) * kstep;
;             const char* a2 = last ? nA : cA + (size_t)(t + 2) * kstep; const char* b2 = last ? nB : cB + (size_t)(t + 2) * kstep;
;     ...
;         for (int a = 0; a < 2; ++a)
; #pragma unroll
;             for (int b = 0; b < 2; ++b)
; #pragma unroll
;                 for (int m = 0; m < 4; ++m)
; #pragma unroll
;                     for (int n = 0; n < 2; ++n) acc[a][b][m][n] = (f32x4){0.f, 0.f, 0.f, 0.f};
.LBB0_285:
	s_add_u32 s55, s24, 0x100
	v_mov_b32_e32 v0, 0
	s_addc_u32 s56, s25, 0
	s_mov_b32 s57, -2
	v_mov_b32_e32 v1, v0
	v_mov_b32_e32 v2, v0
	v_mov_b32_e32 v3, v0
	v_mov_b32_e32 v4, v0
	v_mov_b32_e32 v5, v0
	v_mov_b32_e32 v6, v0
	v_mov_b32_e32 v7, v0
	v_mov_b32_e32 v12, v0
	v_mov_b32_e32 v13, v0
	v_mov_b32_e32 v14, v0
	v_mov_b32_e32 v15, v0
	v_mov_b32_e32 v20, v0
	v_mov_b32_e32 v21, v0
	v_mov_b32_e32 v22, v0
	v_mov_b32_e32 v23, v0
	v_mov_b32_e32 v28, v0
	v_mov_b32_e32 v29, v0
	v_mov_b32_e32 v30, v0
	v_mov_b32_e32 v31, v0
	v_mov_b32_e32 v36, v0
	v_mov_b32_e32 v37, v0
	v_mov_b32_e32 v38, v0
	v_mov_b32_e32 v39, v0
	v_mov_b32_e32 v44, v0
	v_mov_b32_e32 v45, v0
	v_mov_b32_e32 v46, v0
	v_mov_b32_e32 v47, v0
	v_mov_b32_e32 v52, v0
	v_mov_b32_e32 v53, v0
	v_mov_b32_e32 v54, v0
	v_mov_b32_e32 v55, v0
	v_mov_b32_e32 v8, v0
	v_mov_b32_e32 v9, v0
	v_mov_b32_e32 v10, v0
	v_mov_b32_e32 v11, v0
	v_mov_b32_e32 v16, v0
	v_mov_b32_e32 v17, v0
	v_mov_b32_e32 v18, v0
	v_mov_b32_e32 v19, v0
	v_mov_b32_e32 v24, v0
	v_mov_b32_e32 v25, v0
	v_mov_b32_e32 v26, v0
	v_mov_b32_e32 v27, v0
	v_mov_b32_e32 v32, v0
	v_mov_b32_e32 v33, v0
	v_mov_b32_e32 v34, v0
	v_mov_b32_e32 v35, v0
	v_mov_b32_e32 v40, v0
	v_mov_b32_e32 v41, v0
	v_mov_b32_e32 v42, v0
	v_mov_b32_e32 v43, v0
	v_mov_b32_e32 v48, v0
	v_mov_b32_e32 v49, v0
	v_mov_b32_e32 v50, v0
	v_mov_b32_e32 v51, v0
	v_mov_b32_e32 v56, v0
	v_mov_b32_e32 v57, v0
	v_mov_b32_e32 v58, v0
	v_mov_b32_e32 v59, v0
	v_mov_b32_e32 v60, v0
	v_mov_b32_e32 v61, v0
	v_mov_b32_e32 v62, v0
	v_mov_b32_e32 v63, v0
	v_mov_b32_e32 v64, v0
	v_mov_b32_e32 v65, v0
	v_mov_b32_e32 v66, v0
	v_mov_b32_e32 v67, v0
	v_mov_b32_e32 v68, v0
	v_mov_b32_e32 v69, v0
	v_mov_b32_e32 v70, v0
	v_mov_b32_e32 v71, v0
	v_mov_b32_e32 v80, v0
	v_mov_b32_e32 v81, v0
	v_mov_b32_e32 v82, v0
	v_mov_b32_e32 v83, v0
	v_mov_b32_e32 v84, v0
	v_mov_b32_e32 v85, v0
	v_mov_b32_e32 v86, v0
	v_mov_b32_e32 v87, v0
	v_mov_b32_e32 v96, v0
	v_mov_b32_e32 v97, v0
	v_mov_b32_e32 v98, v0
	v_mov_b32_e32 v99, v0
	v_mov_b32_e32 v100, v0
	v_mov_b32_e32 v101, v0
	v_mov_b32_e32 v102, v0
	v_mov_b32_e32 v103, v0
	v_mov_b32_e32 v112, v0
	v_mov_b32_e32 v113, v0
	v_mov_b32_e32 v114, v0
	v_mov_b32_e32 v115, v0
	v_mov_b32_e32 v116, v0
	v_mov_b32_e32 v117, v0
	v_mov_b32_e32 v118, v0
	v_mov_b32_e32 v119, v0
	v_mov_b32_e32 v72, v0
	v_mov_b32_e32 v73, v0
	v_mov_b32_e32 v74, v0
	v_mov_b32_e32 v75, v0
	v_mov_b32_e32 v76, v0
	v_mov_b32_e32 v77, v0
	v_mov_b32_e32 v78, v0
	v_mov_b32_e32 v79, v0
	v_mov_b32_e32 v88, v0
	v_mov_b32_e32 v89, v0
	v_mov_b32_e32 v90, v0
	v_mov_b32_e32 v91, v0
	v_mov_b32_e32 v92, v0
	v_mov_b32_e32 v93, v0
	v_mov_b32_e32 v94, v0
	v_mov_b32_e32 v95, v0
	v_mov_b32_e32 v104, v0
	v_mov_b32_e32 v105, v0
	v_mov_b32_e32 v106, v0
	v_mov_b32_e32 v107, v0
	v_mov_b32_e32 v108, v0
	v_mov_b32_e32 v109, v0
	v_mov_b32_e32 v110, v0
	v_mov_b32_e32 v111, v0
	v_mov_b32_e32 v120, v0
	v_mov_b32_e32 v121, v0
	v_mov_b32_e32 v122, v0
	v_mov_b32_e32 v123, v0
	v_mov_b32_e32 v124, v0
	v_mov_b32_e32 v125, v0
	v_mov_b32_e32 v126, v0
	v_mov_b32_e32 v127, v0
	.p2align 6

; template <class Epi, class Sched>
; __device__ __forceinline__ void gemm_phase(PG8_LAS unsigned char* lds, const Gemm g, const Sched& S, const Epi& E) {
;     ...
;         const bool has_next = S.next(ui + 1, nxt);
;         const char* nA = has_next ? (const char*)g.A + (size_t)nxt.pm * tstep : cA; const char* nB = has_next ? (const char*)g.Bt + (size_t)nxt.pn * tstep : cB;
;         for (int t = 0; t < nt; t += 2) {
;             const bool last = (t == nt - 2);
;             const char* a1 = cA + (size_t)(t + 1) * kstep;
;             const char* a2 = last ? nA : cA + (size_t)(t + 2) * kstep; const char* b2 = last ? nB : cB + (size_t)(t + 2) * kstep;
;     ...
;         for (int a = 0; a < 2; ++a)
; #pragma unroll
;             for (int b = 0; b < 2; ++b)
; #pragma unroll
;                 for (int m = 0; m < 4; ++m)
; #pragma unroll
;                     for (int n = 0; n < 2; ++n) acc[a][b][m][n] = (f32x4){0.f, 0.f, 0.f, 0.f};
.LBB0_415:
	s_ashr_i32 s21, s20, 31
	v_cmp_lt_i64_e32 vcc, s[22:23], v[170:171]
	s_lshl_b64 s[22:23], s[20:21], 19
	s_add_u32 s22, s31, s22
	s_addc_u32 s23, s34, s23
	s_and_b64 s[24:25], vcc, exec
	s_cselect_b32 s7, s23, s1
	s_cselect_b32 s10, s22, s0
	s_ashr_i32 s19, s18, 31
	s_lshl_b64 s[24:25], s[18:19], 19
	s_add_u32 s24, s8, s24
	s_addc_u32 s25, s9, s25
	s_and_b64 s[28:29], vcc, exec
	s_cselect_b32 s19, s25, s5
	s_cselect_b32 s21, s24, s4
	s_add_u32 s0, s0, 0x40080
	s_addc_u32 s1, s1, 0
	s_add_u32 s51, s4, 0x100
	v_mov_b32_e32 v0, 0
	s_addc_u32 s52, s5, 0
	s_mov_b32 s53, -2
	v_mov_b32_e32 v1, v0
	v_mov_b32_e32 v2, v0
	v_mov_b32_e32 v3, v0
	v_mov_b32_e32 v4, v0
	v_mov_b32_e32 v5, v0
	v_mov_b32_e32 v6, v0
	v_mov_b32_e32 v7, v0
	v_mov_b32_e32 v16, v0
	v_mov_b32_e32 v17, v0
	v_mov_b32_e32 v18, v0
	v_mov_b32_e32 v19, v0
	v_mov_b32_e32 v20, v0
	v_mov_b32_e32 v21, v0
	v_mov_b32_e32 v22, v0
	v_mov_b32_e32 v23, v0
	v_mov_b32_e32 v48, v0
	v_mov_b32_e32 v49, v0
	v_mov_b32_e32 v50, v0
	v_mov_b32_e32 v51, v0
	v_mov_b32_e32 v52, v0
	v_mov_b32_e32 v53, v0
	v_mov_b32_e32 v54, v0
	v_mov_b32_e32 v55, v0
	v_mov_b32_e32 v64, v0
	v_mov_b32_e32 v65, v0
	v_mov_b32_e32 v66, v0
	v_mov_b32_e32 v67, v0
	v_mov_b32_e32 v68, v0
	v_mov_b32_e32 v69, v0
	v_mov_b32_e32 v70, v0
	v_mov_b32_e32 v71, v0
	v_mov_b32_e32 v8, v0
	v_mov_b32_e32 v9, v0
	v_mov_b32_e32 v10, v0
	v_mov_b32_e32 v11, v0
	v_mov_b32_e32 v12, v0
	v_mov_b32_e32 v13, v0
	v_mov_b32_e32 v14, v0
	v_mov_b32_e32 v15, v0
	v_mov_b32_e32 v32, v0
	v_mov_b32_e32 v33, v0
	v_mov_b32_e32 v34, v0
	v_mov_b32_e32 v35, v0
	v_mov_b32_e32 v36, v0
	v_mov_b32_e32 v37, v0
	v_mov_b32_e32 v38, v0
	v_mov_b32_e32 v39, v0
	v_mov_b32_e32 v56, v0
	v_mov_b32_e32 v57, v0
	v_mov_b32_e32 v58, v0
	v_mov_b32_e32 v59, v0
	v_mov_b32_e32 v60, v0
	v_mov_b32_e32 v61, v0
	v_mov_b32_e32 v62, v0
	v_mov_b32_e32 v63, v0
	v_mov_b32_e32 v72, v0
	v_mov_b32_e32 v73, v0
	v_mov_b32_e32 v74, v0
	v_mov_b32_e32 v75, v0
	v_mov_b32_e32 v76, v0
	v_mov_b32_e32 v77, v0
	v_mov_b32_e32 v78, v0
	v_mov_b32_e32 v79, v0
	v_mov_b32_e32 v80, v0
	v_mov_b32_e32 v81, v0
	v_mov_b32_e32 v82, v0
	v_mov_b32_e32 v83, v0
	v_mov_b32_e32 v84, v0
	v_mov_b32_e32 v85, v0
	v_mov_b32_e32 v86, v0
	v_mov_b32_e32 v87, v0
	v_mov_b32_e32 v96, v0
	v_mov_b32_e32 v97, v0
	v_mov_b32_e32 v98, v0
	v_mov_b32_e32 v99, v0
	v_mov_b32_e32 v100, v0
	v_mov_b32_e32 v101, v0
	v_mov_b32_e32 v102, v0
	v_mov_b32_e32 v103, v0
	v_mov_b32_e32 v112, v0
	v_mov_b32_e32 v113, v0
	v_mov_b32_e32 v114, v0
	v_mov_b32_e32 v115, v0
	v_mov_b32_e32 v116, v0
	v_mov_b32_e32 v117, v0
	v_mov_b32_e32 v118, v0
	v_mov_b32_e32 v119, v0
	v_mov_b32_e32 v128, v0
	v_mov_b32_e32 v129, v0
	v_mov_b32_e32 v130, v0
	v_mov_b32_e32 v131, v0
	v_mov_b32_e32 v132, v0
	v_mov_b32_e32 v133, v0
	v_mov_b32_e32 v134, v0
	v_mov_b32_e32 v135, v0
	v_mov_b32_e32 v88, v0
	v_mov_b32_e32 v89, v0
	v_mov_b32_e32 v90, v0
	v_mov_b32_e32 v91, v0
	v_mov_b32_e32 v92, v0
	v_mov_b32_e32 v93, v0
	v_mov_b32_e32 v94, v0
	v_mov_b32_e32 v95, v0
	v_mov_b32_e32 v104, v0
	v_mov_b32_e32 v105, v0
	v_mov_b32_e32 v106, v0
	v_mov_b32_e32 v107, v0
	v_mov_b32_e32 v108, v0
	v_mov_b32_e32 v109, v0
	v_mov_b32_e32 v110, v0
	v_mov_b32_e32 v111, v0
	v_mov_b32_e32 v120, v0
	v_mov_b32_e32 v121, v0
	v_mov_b32_e32 v122, v0
	v_mov_b32_e32 v123, v0
	v_mov_b32_e32 v124, v0
	v_mov_b32_e32 v125, v0
	v_mov_b32_e32 v126, v0
	v_mov_b32_e32 v127, v0
	v_mov_b32_e32 v136, v0
	v_mov_b32_e32 v137, v0
	v_mov_b32_e32 v138, v0
	v_mov_b32_e32 v139, v0
	v_mov_b32_e32 v140, v0
	v_mov_b32_e32 v141, v0
	v_mov_b32_e32 v142, v0
	v_mov_b32_e32 v143, v0
	.p2align 6

; template <class Epi, class Sched>
; __device__ __forceinline__ void gemm_phase(PG8_LAS unsigned char* lds, const Gemm g, const Sched& S, const Epi& E) {
;     ...
;         const bool has_next = S.next(ui + 1, nxt);
;         const char* nA = has_next ? (const char*)g.A + (size_t)nxt.pm * tstep : cA; const char* nB = has_next ? (const char*)g.Bt + (size_t)nxt.pn * tstep : cB;
;         for (int t = 0; t < nt; t += 2) {
;             const bool last = (t == nt - 2);
;             const char* a1 = cA + (size_t)(t + 1) * kstep;
;             const char* a2 = last ? nA : cA + (size_t)(t + 2) * kstep; const char* b2 = last ? nB : cB + (size_t)(t + 2) * kstep;
;     ...
;         for (int a = 0; a < 2; ++a)
; #pragma unroll
;             for (int b = 0; b < 2; ++b)
; #pragma unroll
;                 for (int m = 0; m < 4; ++m)
; #pragma unroll
;                     for (int n = 0; n < 2; ++n) acc[a][b][m][n] = (f32x4){0.f, 0.f, 0.f, 0.f};
.LBB0_723:
	s_ashr_i32 s11, s10, 31
	v_cmp_lt_i64_e32 vcc, s[12:13], v[140:141]
	s_lshl_b64 s[12:13], s[10:11], 19
	s_add_u32 s12, s26, s12
	s_addc_u32 s13, s27, s13
	s_and_b64 s[14:15], vcc, exec
	s_cselect_b32 s5, s13, s19
	s_cselect_b32 s11, s12, s18
	s_ashr_i32 s9, s8, 31
	s_lshl_b64 s[14:15], s[8:9], 19
	s_add_u32 s14, s28, s14
	s_addc_u32 s15, s29, s15
	s_and_b64 s[22:23], vcc, exec
	s_cselect_b32 s9, s15, s21
	s_cselect_b32 s45, s14, s20
	s_add_u32 s18, s18, 0x40080
	s_addc_u32 s19, s19, 0
	s_add_u32 s46, s20, 0x100
	v_mov_b32_e32 v0, 0
	s_addc_u32 s47, s21, 0
	s_mov_b32 s48, -2
	v_mov_b32_e32 v1, v0
	v_mov_b32_e32 v2, v0
	v_mov_b32_e32 v3, v0
	v_mov_b32_e32 v4, v0
	v_mov_b32_e32 v5, v0
	v_mov_b32_e32 v6, v0
	v_mov_b32_e32 v7, v0
	v_mov_b32_e32 v16, v0
	v_mov_b32_e32 v17, v0
	v_mov_b32_e32 v18, v0
	v_mov_b32_e32 v19, v0
	v_mov_b32_e32 v20, v0
	v_mov_b32_e32 v21, v0
	v_mov_b32_e32 v22, v0
	v_mov_b32_e32 v23, v0
	v_mov_b32_e32 v32, v0
	v_mov_b32_e32 v33, v0
	v_mov_b32_e32 v34, v0
	v_mov_b32_e32 v35, v0
	v_mov_b32_e32 v36, v0
	v_mov_b32_e32 v37, v0
	v_mov_b32_e32 v38, v0
	v_mov_b32_e32 v39, v0
	v_mov_b32_e32 v48, v0
	v_mov_b32_e32 v49, v0
	v_mov_b32_e32 v50, v0
	v_mov_b32_e32 v51, v0
	v_mov_b32_e32 v52, v0
	v_mov_b32_e32 v53, v0
	v_mov_b32_e32 v54, v0
	v_mov_b32_e32 v55, v0
	v_mov_b32_e32 v8, v0
	v_mov_b32_e32 v9, v0
	v_mov_b32_e32 v10, v0
	v_mov_b32_e32 v11, v0
	v_mov_b32_e32 v12, v0
	v_mov_b32_e32 v13, v0
	v_mov_b32_e32 v14, v0
	v_mov_b32_e32 v15, v0
	v_mov_b32_e32 v24, v0
	v_mov_b32_e32 v25, v0
	v_mov_b32_e32 v26, v0
	v_mov_b32_e32 v27, v0
	v_mov_b32_e32 v28, v0
	v_mov_b32_e32 v29, v0
	v_mov_b32_e32 v30, v0
	v_mov_b32_e32 v31, v0
	v_mov_b32_e32 v40, v0
	v_mov_b32_e32 v41, v0
	v_mov_b32_e32 v42, v0
	v_mov_b32_e32 v43, v0
	v_mov_b32_e32 v44, v0
	v_mov_b32_e32 v45, v0
	v_mov_b32_e32 v46, v0
	v_mov_b32_e32 v47, v0
	v_mov_b32_e32 v56, v0
	v_mov_b32_e32 v57, v0
	v_mov_b32_e32 v58, v0
	v_mov_b32_e32 v59, v0
	v_mov_b32_e32 v60, v0
	v_mov_b32_e32 v61, v0
	v_mov_b32_e32 v62, v0
	v_mov_b32_e32 v63, v0
	v_mov_b32_e32 v64, v0
	v_mov_b32_e32 v65, v0
	v_mov_b32_e32 v66, v0
	v_mov_b32_e32 v67, v0
	v_mov_b32_e32 v68, v0
	v_mov_b32_e32 v69, v0
	v_mov_b32_e32 v70, v0
	v_mov_b32_e32 v71, v0
	v_mov_b32_e32 v80, v0
	v_mov_b32_e32 v81, v0
	v_mov_b32_e32 v82, v0
	v_mov_b32_e32 v83, v0
	v_mov_b32_e32 v84, v0
	v_mov_b32_e32 v85, v0
	v_mov_b32_e32 v86, v0
	v_mov_b32_e32 v87, v0
	v_mov_b32_e32 v96, v0
	v_mov_b32_e32 v97, v0
	v_mov_b32_e32 v98, v0
	v_mov_b32_e32 v99, v0
	v_mov_b32_e32 v100, v0
	v_mov_b32_e32 v101, v0
	v_mov_b32_e32 v102, v0
	v_mov_b32_e32 v103, v0
	v_mov_b32_e32 v112, v0
	v_mov_b32_e32 v113, v0
	v_mov_b32_e32 v114, v0
	v_mov_b32_e32 v115, v0
	v_mov_b32_e32 v116, v0
	v_mov_b32_e32 v117, v0
	v_mov_b32_e32 v118, v0
	v_mov_b32_e32 v119, v0
	v_mov_b32_e32 v72, v0
	v_mov_b32_e32 v73, v0
	v_mov_b32_e32 v74, v0
	v_mov_b32_e32 v75, v0
	v_mov_b32_e32 v76, v0
	v_mov_b32_e32 v77, v0
	v_mov_b32_e32 v78, v0
	v_mov_b32_e32 v79, v0
	v_mov_b32_e32 v88, v0
	v_mov_b32_e32 v89, v0
	v_mov_b32_e32 v90, v0
	v_mov_b32_e32 v91, v0
	v_mov_b32_e32 v92, v0
	v_mov_b32_e32 v93, v0
	v_mov_b32_e32 v94, v0
	v_mov_b32_e32 v95, v0
	v_mov_b32_e32 v104, v0
	v_mov_b32_e32 v105, v0
	v_mov_b32_e32 v106, v0
	v_mov_b32_e32 v107, v0
	v_mov_b32_e32 v108, v0
	v_mov_b32_e32 v109, v0
	v_mov_b32_e32 v110, v0
	v_mov_b32_e32 v111, v0
	v_mov_b32_e32 v120, v0
	v_mov_b32_e32 v121, v0
	v_mov_b32_e32 v122, v0
	v_mov_b32_e32 v123, v0
	v_mov_b32_e32 v124, v0
	v_mov_b32_e32 v125, v0
	v_mov_b32_e32 v126, v0
	v_mov_b32_e32 v127, v0
	.p2align 6

; template <class Epi, class Sched>
; __device__ __forceinline__ void gemm_phase(PG8_LAS unsigned char* lds, const Gemm g, const Sched& S, const Epi& E) {
;     ...
;         const bool has_next = S.next(ui + 1, nxt);
;         const char* nA = has_next ? (const char*)g.A + (size_t)nxt.pm * tstep : cA; const char* nB = has_next ? (const char*)g.Bt + (size_t)nxt.pn * tstep : cB;
;         for (int t = 0; t < nt; t += 2) {
;             const bool last = (t == nt - 2);
;             const char* a1 = cA + (size_t)(t + 1) * kstep;
;             const char* a2 = last ? nA : cA + (size_t)(t + 2) * kstep; const char* b2 = last ? nB : cB + (size_t)(t + 2) * kstep;
;     ...
;         for (int a = 0; a < 2; ++a)
; #pragma unroll
;             for (int b = 0; b < 2; ++b)
; #pragma unroll
;                 for (int m = 0; m < 4; ++m)
; #pragma unroll
;                     for (int n = 0; n < 2; ++n) acc[a][b][m][n] = (f32x4){0.f, 0.f, 0.f, 0.f};
.LBB0_990:
	s_ashr_i32 s11, s10, 31
	v_cmp_lt_i64_e32 vcc, s[12:13], v[140:141]
	s_lshl_b64 s[12:13], s[10:11], 19
	s_add_u32 s12, s27, s12
	s_addc_u32 s13, s28, s13
	s_and_b64 s[14:15], vcc, exec
	s_cselect_b32 s11, s13, s19
	s_cselect_b32 s43, s12, s18
	s_ashr_i32 s9, s8, 31
	s_lshl_b64 s[14:15], s[8:9], 19
	s_add_u32 s14, s96, s14
	s_addc_u32 s15, s97, s15
	s_and_b64 s[22:23], vcc, exec
	s_cselect_b32 s9, s15, s21
	s_cselect_b32 s44, s14, s20
	s_add_u32 s18, s18, 0x40080
	s_addc_u32 s19, s19, 0
	s_add_u32 s45, s20, 0x100
	v_mov_b32_e32 v0, 0
	s_addc_u32 s46, s21, 0
	s_mov_b32 s47, -2
	v_mov_b32_e32 v1, v0
	v_mov_b32_e32 v2, v0
	v_mov_b32_e32 v3, v0
	v_mov_b32_e32 v4, v0
	v_mov_b32_e32 v5, v0
	v_mov_b32_e32 v6, v0
	v_mov_b32_e32 v7, v0
	v_mov_b32_e32 v12, v0
	v_mov_b32_e32 v13, v0
	v_mov_b32_e32 v14, v0
	v_mov_b32_e32 v15, v0
	v_mov_b32_e32 v20, v0
	v_mov_b32_e32 v21, v0
	v_mov_b32_e32 v22, v0
	v_mov_b32_e32 v23, v0
	v_mov_b32_e32 v28, v0
	v_mov_b32_e32 v29, v0
	v_mov_b32_e32 v30, v0
	v_mov_b32_e32 v31, v0
	v_mov_b32_e32 v36, v0
	v_mov_b32_e32 v37, v0
	v_mov_b32_e32 v38, v0
	v_mov_b32_e32 v39, v0
	v_mov_b32_e32 v44, v0
	v_mov_b32_e32 v45, v0
	v_mov_b32_e32 v46, v0
	v_mov_b32_e32 v47, v0
	v_mov_b32_e32 v52, v0
	v_mov_b32_e32 v53, v0
	v_mov_b32_e32 v54, v0
	v_mov_b32_e32 v55, v0
	v_mov_b32_e32 v8, v0
	v_mov_b32_e32 v9, v0
	v_mov_b32_e32 v10, v0
	v_mov_b32_e32 v11, v0
	v_mov_b32_e32 v16, v0
	v_mov_b32_e32 v17, v0
	v_mov_b32_e32 v18, v0
	v_mov_b32_e32 v19, v0
	v_mov_b32_e32 v24, v0
	v_mov_b32_e32 v25, v0
	v_mov_b32_e32 v26, v0
	v_mov_b32_e32 v27, v0
	v_mov_b32_e32 v32, v0
	v_mov_b32_e32 v33, v0
	v_mov_b32_e32 v34, v0
	v_mov_b32_e32 v35, v0
	v_mov_b32_e32 v40, v0
	v_mov_b32_e32 v41, v0
	v_mov_b32_e32 v42, v0
	v_mov_b32_e32 v43, v0
	v_mov_b32_e32 v48, v0
	v_mov_b32_e32 v49, v0
	v_mov_b32_e32 v50, v0
	v_mov_b32_e32 v51, v0
	v_mov_b32_e32 v56, v0
	v_mov_b32_e32 v57, v0
	v_mov_b32_e32 v58, v0
	v_mov_b32_e32 v59, v0
	v_mov_b32_e32 v60, v0
	v_mov_b32_e32 v61, v0
	v_mov_b32_e32 v62, v0
	v_mov_b32_e32 v63, v0
	v_mov_b32_e32 v64, v0
	v_mov_b32_e32 v65, v0
	v_mov_b32_e32 v66, v0
	v_mov_b32_e32 v67, v0
	v_mov_b32_e32 v68, v0
	v_mov_b32_e32 v69, v0
	v_mov_b32_e32 v70, v0
	v_mov_b32_e32 v71, v0
	v_mov_b32_e32 v76, v0
	v_mov_b32_e32 v77, v0
	v_mov_b32_e32 v78, v0
	v_mov_b32_e32 v79, v0
	v_mov_b32_e32 v84, v0
	v_mov_b32_e32 v85, v0
	v_mov_b32_e32 v86, v0
	v_mov_b32_e32 v87, v0
	v_mov_b32_e32 v92, v0
	v_mov_b32_e32 v93, v0
	v_mov_b32_e32 v94, v0
	v_mov_b32_e32 v95, v0
	v_mov_b32_e32 v100, v0
	v_mov_b32_e32 v101, v0
	v_mov_b32_e32 v102, v0
	v_mov_b32_e32 v103, v0
	v_mov_b32_e32 v108, v0
	v_mov_b32_e32 v109, v0
	v_mov_b32_e32 v110, v0
	v_mov_b32_e32 v111, v0
	v_mov_b32_e32 v116, v0
	v_mov_b32_e32 v117, v0
	v_mov_b32_e32 v118, v0
	v_mov_b32_e32 v119, v0
	v_mov_b32_e32 v72, v0
	v_mov_b32_e32 v73, v0
	v_mov_b32_e32 v74, v0
	v_mov_b32_e32 v75, v0
	v_mov_b32_e32 v80, v0
	v_mov_b32_e32 v81, v0
	v_mov_b32_e32 v82, v0
	v_mov_b32_e32 v83, v0
	v_mov_b32_e32 v88, v0
	v_mov_b32_e32 v89, v0
	v_mov_b32_e32 v90, v0
	v_mov_b32_e32 v91, v0
	v_mov_b32_e32 v96, v0
	v_mov_b32_e32 v97, v0
	v_mov_b32_e32 v98, v0
	v_mov_b32_e32 v99, v0
	v_mov_b32_e32 v104, v0
	v_mov_b32_e32 v105, v0
	v_mov_b32_e32 v106, v0
	v_mov_b32_e32 v107, v0
	v_mov_b32_e32 v112, v0
	v_mov_b32_e32 v113, v0
	v_mov_b32_e32 v114, v0
	v_mov_b32_e32 v115, v0
	v_mov_b32_e32 v120, v0
	v_mov_b32_e32 v121, v0
	v_mov_b32_e32 v122, v0
	v_mov_b32_e32 v123, v0
	v_mov_b32_e32 v124, v0
	v_mov_b32_e32 v125, v0
	v_mov_b32_e32 v126, v0
	v_mov_b32_e32 v127, v0
	.p2align 6

; template <class Epi, class Sched>
; __device__ __forceinline__ void gemm_phase(PG8_LAS unsigned char* lds, const Gemm g, const Sched& S, const Epi& E) {
;     ...
;         const bool has_next = S.next(ui + 1, nxt);
;         const char* nA = has_next ? (const char*)g.A + (size_t)nxt.pm * tstep : cA; const char* nB = has_next ? (const char*)g.Bt + (size_t)nxt.pn * tstep : cB;
;         for (int t = 0; t < nt; t += 2) {
;             const bool last = (t == nt - 2);
;             const char* a1 = cA + (size_t)(t + 1) * kstep;
;             const char* a2 = last ? nA : cA + (size_t)(t + 2) * kstep; const char* b2 = last ? nB : cB + (size_t)(t + 2) * kstep;
;     ...
;         for (int a = 0; a < 2; ++a)
; #pragma unroll
;             for (int b = 0; b < 2; ++b)
; #pragma unroll
;                 for (int m = 0; m < 4; ++m)
; #pragma unroll
;                     for (int n = 0; n < 2; ++n) acc[a][b][m][n] = (f32x4){0.f, 0.f, 0.f, 0.f};
.LBB0_1010:
	s_ashr_i32 s11, s10, 31
	v_cmp_lt_i64_e32 vcc, s[12:13], v[140:141]
	s_lshl_b64 s[12:13], s[10:11], 19
	s_add_u32 s12, s27, s12
	s_addc_u32 s13, s28, s13
	s_and_b64 s[14:15], vcc, exec
	s_cselect_b32 s11, s13, s19
	s_cselect_b32 s43, s12, s18
	s_ashr_i32 s9, s8, 31
	s_lshl_b64 s[14:15], s[8:9], 19
	s_add_u32 s14, s94, s14
	s_addc_u32 s15, s95, s15
	s_and_b64 s[22:23], vcc, exec
	s_cselect_b32 s9, s15, s21
	s_cselect_b32 s44, s14, s20
	s_add_u32 s18, s18, 0x40080
	s_addc_u32 s19, s19, 0
	s_add_u32 s45, s20, 0x100
	v_mov_b32_e32 v0, 0
	s_addc_u32 s46, s21, 0
	s_mov_b32 s47, -2
	v_mov_b32_e32 v1, v0
	v_mov_b32_e32 v2, v0
	v_mov_b32_e32 v3, v0
	v_mov_b32_e32 v4, v0
	v_mov_b32_e32 v5, v0
	v_mov_b32_e32 v6, v0
	v_mov_b32_e32 v7, v0
	v_mov_b32_e32 v16, v0
	v_mov_b32_e32 v17, v0
	v_mov_b32_e32 v18, v0
	v_mov_b32_e32 v19, v0
	v_mov_b32_e32 v20, v0
	v_mov_b32_e32 v21, v0
	v_mov_b32_e32 v22, v0
	v_mov_b32_e32 v23, v0
	v_mov_b32_e32 v32, v0
	v_mov_b32_e32 v33, v0
	v_mov_b32_e32 v34, v0
	v_mov_b32_e32 v35, v0
	v_mov_b32_e32 v36, v0
	v_mov_b32_e32 v37, v0
	v_mov_b32_e32 v38, v0
	v_mov_b32_e32 v39, v0
	v_mov_b32_e32 v48, v0
	v_mov_b32_e32 v49, v0
	v_mov_b32_e32 v50, v0
	v_mov_b32_e32 v51, v0
	v_mov_b32_e32 v52, v0
	v_mov_b32_e32 v53, v0
	v_mov_b32_e32 v54, v0
	v_mov_b32_e32 v55, v0
	v_mov_b32_e32 v8, v0
	v_mov_b32_e32 v9, v0
	v_mov_b32_e32 v10, v0
	v_mov_b32_e32 v11, v0
	v_mov_b32_e32 v12, v0
	v_mov_b32_e32 v13, v0
	v_mov_b32_e32 v14, v0
	v_mov_b32_e32 v15, v0
	v_mov_b32_e32 v24, v0
	v_mov_b32_e32 v25, v0
	v_mov_b32_e32 v26, v0
	v_mov_b32_e32 v27, v0
	v_mov_b32_e32 v28, v0
	v_mov_b32_e32 v29, v0
	v_mov_b32_e32 v30, v0
	v_mov_b32_e32 v31, v0
	v_mov_b32_e32 v40, v0
	v_mov_b32_e32 v41, v0
	v_mov_b32_e32 v42, v0
	v_mov_b32_e32 v43, v0
	v_mov_b32_e32 v44, v0
	v_mov_b32_e32 v45, v0
	v_mov_b32_e32 v46, v0
	v_mov_b32_e32 v47, v0
	v_mov_b32_e32 v56, v0
	v_mov_b32_e32 v57, v0
	v_mov_b32_e32 v58, v0
	v_mov_b32_e32 v59, v0
	v_mov_b32_e32 v60, v0
	v_mov_b32_e32 v61, v0
	v_mov_b32_e32 v62, v0
	v_mov_b32_e32 v63, v0
	v_mov_b32_e32 v64, v0
	v_mov_b32_e32 v65, v0
	v_mov_b32_e32 v66, v0
	v_mov_b32_e32 v67, v0
	v_mov_b32_e32 v68, v0
	v_mov_b32_e32 v69, v0
	v_mov_b32_e32 v70, v0
	v_mov_b32_e32 v71, v0
	v_mov_b32_e32 v80, v0
	v_mov_b32_e32 v81, v0
	v_mov_b32_e32 v82, v0
	v_mov_b32_e32 v83, v0
	v_mov_b32_e32 v84, v0
	v_mov_b32_e32 v85, v0
	v_mov_b32_e32 v86, v0
	v_mov_b32_e32 v87, v0
	v_mov_b32_e32 v96, v0
	v_mov_b32_e32 v97, v0
	v_mov_b32_e32 v98, v0
	v_mov_b32_e32 v99, v0
	v_mov_b32_e32 v100, v0
	v_mov_b32_e32 v101, v0
	v_mov_b32_e32 v102, v0
	v_mov_b32_e32 v103, v0
	v_mov_b32_e32 v112, v0
	v_mov_b32_e32 v113, v0
	v_mov_b32_e32 v114, v0
	v_mov_b32_e32 v115, v0
	v_mov_b32_e32 v116, v0
	v_mov_b32_e32 v117, v0
	v_mov_b32_e32 v118, v0
	v_mov_b32_e32 v119, v0
	v_mov_b32_e32 v72, v0
	v_mov_b32_e32 v73, v0
	v_mov_b32_e32 v74, v0
	v_mov_b32_e32 v75, v0
	v_mov_b32_e32 v76, v0
	v_mov_b32_e32 v77, v0
	v_mov_b32_e32 v78, v0
	v_mov_b32_e32 v79, v0
	v_mov_b32_e32 v88, v0
	v_mov_b32_e32 v89, v0
	v_mov_b32_e32 v90, v0
	v_mov_b32_e32 v91, v0
	v_mov_b32_e32 v92, v0
	v_mov_b32_e32 v93, v0
	v_mov_b32_e32 v94, v0
	v_mov_b32_e32 v95, v0
	v_mov_b32_e32 v104, v0
	v_mov_b32_e32 v105, v0
	v_mov_b32_e32 v106, v0
	v_mov_b32_e32 v107, v0
	v_mov_b32_e32 v108, v0
	v_mov_b32_e32 v109, v0
	v_mov_b32_e32 v110, v0
	v_mov_b32_e32 v111, v0
	v_mov_b32_e32 v120, v0
	v_mov_b32_e32 v121, v0
	v_mov_b32_e32 v122, v0
	v_mov_b32_e32 v123, v0
	v_mov_b32_e32 v124, v0
	v_mov_b32_e32 v125, v0
	v_mov_b32_e32 v126, v0
	v_mov_b32_e32 v127, v0
	.p2align 6

; template <class Epi, class Sched>
; __device__ __forceinline__ void gemm_phase(PG8_LAS unsigned char* lds, const Gemm g, const Sched& S, const Epi& E) {
;     ...
;         const bool has_next = S.next(ui + 1, nxt);
;         const char* nA = has_next ? (const char*)g.A + (size_t)nxt.pm * tstep : cA; const char* nB = has_next ? (const char*)g.Bt + (size_t)nxt.pn * tstep : cB;
;         for (int t = 0; t < nt; t += 2) {
;             const bool last = (t == nt - 2);
;             const char* a1 = cA + (size_t)(t + 1) * kstep;
;             const char* a2 = last ? nA : cA + (size_t)(t + 2) * kstep; const char* b2 = last ? nB : cB + (size_t)(t + 2) * kstep;
;     ...
;         for (int a = 0; a < 2; ++a)
; #pragma unroll
;             for (int b = 0; b < 2; ++b)
; #pragma unroll
;                 for (int m = 0; m < 4; ++m)
; #pragma unroll
;                     for (int n = 0; n < 2; ++n) acc[a][b][m][n] = (f32x4){0.f, 0.f, 0.f, 0.f};
.LBB0_1082:
	s_ashr_i32 s17, s16, 31
	v_cmp_lt_i64_e32 vcc, s[18:19], v[140:141]
	s_lshl_b64 s[18:19], s[16:17], 19
	s_add_u32 s18, s35, s18
	s_addc_u32 s19, s36, s19
	s_and_b64 s[20:21], vcc, exec
	s_cselect_b32 s17, s19, s25
	s_cselect_b32 s52, s18, s24
	s_ashr_i32 s15, s14, 31
	s_lshl_b64 s[20:21], s[14:15], 19
	s_add_u32 s20, s72, s20
	s_addc_u32 s21, s73, s21
	s_and_b64 s[28:29], vcc, exec
	s_cselect_b32 s15, s21, s27
	s_cselect_b32 s53, s20, s26
	s_add_u32 s24, s24, 0x40080
	s_addc_u32 s25, s25, 0
	s_add_u32 s54, s26, 0x100
	v_mov_b32_e32 v0, 0
	s_addc_u32 s55, s27, 0
	s_mov_b32 s56, -2
	v_mov_b32_e32 v1, v0
	v_mov_b32_e32 v2, v0
	v_mov_b32_e32 v3, v0
	v_mov_b32_e32 v4, v0
	v_mov_b32_e32 v5, v0
	v_mov_b32_e32 v6, v0
	v_mov_b32_e32 v7, v0
	v_mov_b32_e32 v12, v0
	v_mov_b32_e32 v13, v0
	v_mov_b32_e32 v14, v0
	v_mov_b32_e32 v15, v0
	v_mov_b32_e32 v20, v0
	v_mov_b32_e32 v21, v0
	v_mov_b32_e32 v22, v0
	v_mov_b32_e32 v23, v0
	v_mov_b32_e32 v28, v0
	v_mov_b32_e32 v29, v0
	v_mov_b32_e32 v30, v0
	v_mov_b32_e32 v31, v0
	v_mov_b32_e32 v36, v0
	v_mov_b32_e32 v37, v0
	v_mov_b32_e32 v38, v0
	v_mov_b32_e32 v39, v0
	v_mov_b32_e32 v44, v0
	v_mov_b32_e32 v45, v0
	v_mov_b32_e32 v46, v0
	v_mov_b32_e32 v47, v0
	v_mov_b32_e32 v52, v0
	v_mov_b32_e32 v53, v0
	v_mov_b32_e32 v54, v0
	v_mov_b32_e32 v55, v0
	v_mov_b32_e32 v8, v0
	v_mov_b32_e32 v9, v0
	v_mov_b32_e32 v10, v0
	v_mov_b32_e32 v11, v0
	v_mov_b32_e32 v16, v0
	v_mov_b32_e32 v17, v0
	v_mov_b32_e32 v18, v0
	v_mov_b32_e32 v19, v0
	v_mov_b32_e32 v24, v0
	v_mov_b32_e32 v25, v0
	v_mov_b32_e32 v26, v0
	v_mov_b32_e32 v27, v0
	v_mov_b32_e32 v32, v0
	v_mov_b32_e32 v33, v0
	v_mov_b32_e32 v34, v0
	v_mov_b32_e32 v35, v0
	v_mov_b32_e32 v40, v0
	v_mov_b32_e32 v41, v0
	v_mov_b32_e32 v42, v0
	v_mov_b32_e32 v43, v0
	v_mov_b32_e32 v48, v0
	v_mov_b32_e32 v49, v0
	v_mov_b32_e32 v50, v0
	v_mov_b32_e32 v51, v0
	v_mov_b32_e32 v56, v0
	v_mov_b32_e32 v57, v0
	v_mov_b32_e32 v58, v0
	v_mov_b32_e32 v59, v0
	v_mov_b32_e32 v60, v0
	v_mov_b32_e32 v61, v0
	v_mov_b32_e32 v62, v0
	v_mov_b32_e32 v63, v0
	v_mov_b32_e32 v64, v0
	v_mov_b32_e32 v65, v0
	v_mov_b32_e32 v66, v0
	v_mov_b32_e32 v67, v0
	v_mov_b32_e32 v68, v0
	v_mov_b32_e32 v69, v0
	v_mov_b32_e32 v70, v0
	v_mov_b32_e32 v71, v0
	v_mov_b32_e32 v80, v0
	v_mov_b32_e32 v81, v0
	v_mov_b32_e32 v82, v0
	v_mov_b32_e32 v83, v0
	v_mov_b32_e32 v84, v0
	v_mov_b32_e32 v85, v0
	v_mov_b32_e32 v86, v0
	v_mov_b32_e32 v87, v0
	v_mov_b32_e32 v96, v0
	v_mov_b32_e32 v97, v0
	v_mov_b32_e32 v98, v0
	v_mov_b32_e32 v99, v0
	v_mov_b32_e32 v100, v0
	v_mov_b32_e32 v101, v0
	v_mov_b32_e32 v102, v0
	v_mov_b32_e32 v103, v0
	v_mov_b32_e32 v112, v0
	v_mov_b32_e32 v113, v0
	v_mov_b32_e32 v114, v0
	v_mov_b32_e32 v115, v0
	v_mov_b32_e32 v116, v0
	v_mov_b32_e32 v117, v0
	v_mov_b32_e32 v118, v0
	v_mov_b32_e32 v119, v0
	v_mov_b32_e32 v72, v0
	v_mov_b32_e32 v73, v0
	v_mov_b32_e32 v74, v0
	v_mov_b32_e32 v75, v0
	v_mov_b32_e32 v76, v0
	v_mov_b32_e32 v77, v0
	v_mov_b32_e32 v78, v0
	v_mov_b32_e32 v79, v0
	v_mov_b32_e32 v88, v0
	v_mov_b32_e32 v89, v0
	v_mov_b32_e32 v90, v0
	v_mov_b32_e32 v91, v0
	v_mov_b32_e32 v92, v0
	v_mov_b32_e32 v93, v0
	v_mov_b32_e32 v94, v0
	v_mov_b32_e32 v95, v0
	v_mov_b32_e32 v104, v0
	v_mov_b32_e32 v105, v0
	v_mov_b32_e32 v106, v0
	v_mov_b32_e32 v107, v0
	v_mov_b32_e32 v108, v0
	v_mov_b32_e32 v109, v0
	v_mov_b32_e32 v110, v0
	v_mov_b32_e32 v111, v0
	v_mov_b32_e32 v120, v0
	v_mov_b32_e32 v121, v0
	v_mov_b32_e32 v122, v0
	v_mov_b32_e32 v123, v0
	v_mov_b32_e32 v124, v0
	v_mov_b32_e32 v125, v0
	v_mov_b32_e32 v126, v0
	v_mov_b32_e32 v127, v0
	.p2align 6

; template <class Epi, class Sched>
; __device__ __forceinline__ void gemm_phase(PG8_LAS unsigned char* lds, const Gemm g, const Sched& S, const Epi& E) {
;     ...
;         const bool has_next = S.next(ui + 1, nxt);
;         const char* nA = has_next ? (const char*)g.A + (size_t)nxt.pm * tstep : cA; const char* nB = has_next ? (const char*)g.Bt + (size_t)nxt.pn * tstep : cB;
;         for (int t = 0; t < nt; t += 2) {
;             const bool last = (t == nt - 2);
;             const char* a1 = cA + (size_t)(t + 1) * kstep;
;             const char* a2 = last ? nA : cA + (size_t)(t + 2) * kstep; const char* b2 = last ? nB : cB + (size_t)(t + 2) * kstep;
;     ...
;         for (int a = 0; a < 2; ++a)
; #pragma unroll
;             for (int b = 0; b < 2; ++b)
; #pragma unroll
;                 for (int m = 0; m < 4; ++m)
; #pragma unroll
;                     for (int n = 0; n < 2; ++n) acc[a][b][m][n] = (f32x4){0.f, 0.f, 0.f, 0.f};
.LBB0_1201:
	s_ashr_i32 s9, s8, 31
	v_cmp_lt_i64_e32 vcc, s[10:11], v[140:141]
	s_lshl_b64 s[10:11], s[8:9], 19
	s_add_u32 s10, s24, s10
	s_addc_u32 s11, s25, s11
	s_and_b64 s[12:13], vcc, exec
	s_cselect_b32 s9, s11, s17
	s_cselect_b32 s42, s10, s16
	s_ashr_i32 s7, s6, 31
	s_lshl_b64 s[12:13], s[6:7], 19
	s_add_u32 s12, s84, s12
	s_addc_u32 s13, s85, s13
	s_and_b64 s[20:21], vcc, exec
	s_cselect_b32 s7, s13, s19
	s_cselect_b32 s43, s12, s18
	s_add_u32 s16, s16, 0x40080
	s_addc_u32 s17, s17, 0
	s_add_u32 s44, s18, 0x100
	v_mov_b32_e32 v0, 0
	s_addc_u32 s45, s19, 0
	s_mov_b32 s46, -2
	v_mov_b32_e32 v1, v0
	v_mov_b32_e32 v2, v0
	v_mov_b32_e32 v3, v0
	v_mov_b32_e32 v4, v0
	v_mov_b32_e32 v5, v0
	v_mov_b32_e32 v6, v0
	v_mov_b32_e32 v7, v0
	v_mov_b32_e32 v16, v0
	v_mov_b32_e32 v17, v0
	v_mov_b32_e32 v18, v0
	v_mov_b32_e32 v19, v0
	v_mov_b32_e32 v20, v0
	v_mov_b32_e32 v21, v0
	v_mov_b32_e32 v22, v0
	v_mov_b32_e32 v23, v0
	v_mov_b32_e32 v32, v0
	v_mov_b32_e32 v33, v0
	v_mov_b32_e32 v34, v0
	v_mov_b32_e32 v35, v0
	v_mov_b32_e32 v36, v0
	v_mov_b32_e32 v37, v0
	v_mov_b32_e32 v38, v0
	v_mov_b32_e32 v39, v0
	v_mov_b32_e32 v48, v0
	v_mov_b32_e32 v49, v0
	v_mov_b32_e32 v50, v0
	v_mov_b32_e32 v51, v0
	v_mov_b32_e32 v52, v0
	v_mov_b32_e32 v53, v0
	v_mov_b32_e32 v54, v0
	v_mov_b32_e32 v55, v0
	v_mov_b32_e32 v8, v0
	v_mov_b32_e32 v9, v0
	v_mov_b32_e32 v10, v0
	v_mov_b32_e32 v11, v0
	v_mov_b32_e32 v12, v0
	v_mov_b32_e32 v13, v0
	v_mov_b32_e32 v14, v0
	v_mov_b32_e32 v15, v0
	v_mov_b32_e32 v24, v0
	v_mov_b32_e32 v25, v0
	v_mov_b32_e32 v26, v0
	v_mov_b32_e32 v27, v0
	v_mov_b32_e32 v28, v0
	v_mov_b32_e32 v29, v0
	v_mov_b32_e32 v30, v0
	v_mov_b32_e32 v31, v0
	v_mov_b32_e32 v40, v0
	v_mov_b32_e32 v41, v0
	v_mov_b32_e32 v42, v0
	v_mov_b32_e32 v43, v0
	v_mov_b32_e32 v44, v0
	v_mov_b32_e32 v45, v0
	v_mov_b32_e32 v46, v0
	v_mov_b32_e32 v47, v0
	v_mov_b32_e32 v56, v0
	v_mov_b32_e32 v57, v0
	v_mov_b32_e32 v58, v0
	v_mov_b32_e32 v59, v0
	v_mov_b32_e32 v60, v0
	v_mov_b32_e32 v61, v0
	v_mov_b32_e32 v62, v0
	v_mov_b32_e32 v63, v0
	v_mov_b32_e32 v64, v0
	v_mov_b32_e32 v65, v0
	v_mov_b32_e32 v66, v0
	v_mov_b32_e32 v67, v0
	v_mov_b32_e32 v68, v0
	v_mov_b32_e32 v69, v0
	v_mov_b32_e32 v70, v0
	v_mov_b32_e32 v71, v0
	v_mov_b32_e32 v80, v0
	v_mov_b32_e32 v81, v0
	v_mov_b32_e32 v82, v0
	v_mov_b32_e32 v83, v0
	v_mov_b32_e32 v84, v0
	v_mov_b32_e32 v85, v0
	v_mov_b32_e32 v86, v0
	v_mov_b32_e32 v87, v0
	v_mov_b32_e32 v96, v0
	v_mov_b32_e32 v97, v0
	v_mov_b32_e32 v98, v0
	v_mov_b32_e32 v99, v0
	v_mov_b32_e32 v100, v0
	v_mov_b32_e32 v101, v0
	v_mov_b32_e32 v102, v0
	v_mov_b32_e32 v103, v0
	v_mov_b32_e32 v112, v0
	v_mov_b32_e32 v113, v0
	v_mov_b32_e32 v114, v0
	v_mov_b32_e32 v115, v0
	v_mov_b32_e32 v116, v0
	v_mov_b32_e32 v117, v0
	v_mov_b32_e32 v118, v0
	v_mov_b32_e32 v119, v0
	v_mov_b32_e32 v72, v0
	v_mov_b32_e32 v73, v0
	v_mov_b32_e32 v74, v0
	v_mov_b32_e32 v75, v0
	v_mov_b32_e32 v76, v0
	v_mov_b32_e32 v77, v0
	v_mov_b32_e32 v78, v0
	v_mov_b32_e32 v79, v0
	v_mov_b32_e32 v88, v0
	v_mov_b32_e32 v89, v0
	v_mov_b32_e32 v90, v0
	v_mov_b32_e32 v91, v0
	v_mov_b32_e32 v92, v0
	v_mov_b32_e32 v93, v0
	v_mov_b32_e32 v94, v0
	v_mov_b32_e32 v95, v0
	v_mov_b32_e32 v104, v0
	v_mov_b32_e32 v105, v0
	v_mov_b32_e32 v106, v0
	v_mov_b32_e32 v107, v0
	v_mov_b32_e32 v108, v0
	v_mov_b32_e32 v109, v0
	v_mov_b32_e32 v110, v0
	v_mov_b32_e32 v111, v0
	v_mov_b32_e32 v120, v0
	v_mov_b32_e32 v121, v0
	v_mov_b32_e32 v122, v0
	v_mov_b32_e32 v123, v0
	v_mov_b32_e32 v124, v0
	v_mov_b32_e32 v125, v0
	v_mov_b32_e32 v126, v0
	v_mov_b32_e32 v127, v0
	.p2align 6

; template <class Epi, class Sched>
; __device__ __forceinline__ void gemm_phase(PG8_LAS unsigned char* lds, const Gemm g, const Sched& S, const Epi& E) {
;     ...
;         for (int t = 0; t < nt; t += 2) {
;             const bool last = (t == nt - 2);
;             const char* a1 = cA + (size_t)(t + 1) * kstep;
;             const char* a2 = last ? nA : cA + (size_t)(t + 2) * kstep; const char* b2 = last ? nB : cB + (size_t)(t + 2) * kstep;
;     ...
;         for (int a = 0; a < 2; ++a)
; #pragma unroll
;             for (int b = 0; b < 2; ++b)
; #pragma unroll
;                 for (int m = 0; m < 4; ++m)
; #pragma unroll
;                     for (int n = 0; n < 2; ++n) acc[a][b][m][n] = (f32x4){0.f, 0.f, 0.f, 0.f};
.LBB0_1277:
	s_add_u32 s52, s20, 0x100
	v_mov_b32_e32 v0, 0
	s_addc_u32 s53, s21, 0
	s_mov_b32 s54, -2
	v_mov_b32_e32 v1, v0
	v_mov_b32_e32 v2, v0
	v_mov_b32_e32 v3, v0
	v_mov_b32_e32 v4, v0
	v_mov_b32_e32 v5, v0
	v_mov_b32_e32 v6, v0
	v_mov_b32_e32 v7, v0
	v_mov_b32_e32 v12, v0
	v_mov_b32_e32 v13, v0
	v_mov_b32_e32 v14, v0
	v_mov_b32_e32 v15, v0
	v_mov_b32_e32 v20, v0
	v_mov_b32_e32 v21, v0
	v_mov_b32_e32 v22, v0
	v_mov_b32_e32 v23, v0
	v_mov_b32_e32 v28, v0
	v_mov_b32_e32 v29, v0
	v_mov_b32_e32 v30, v0
	v_mov_b32_e32 v31, v0
	v_mov_b32_e32 v36, v0
	v_mov_b32_e32 v37, v0
	v_mov_b32_e32 v38, v0
	v_mov_b32_e32 v39, v0
	v_mov_b32_e32 v44, v0
	v_mov_b32_e32 v45, v0
	v_mov_b32_e32 v46, v0
	v_mov_b32_e32 v47, v0
	v_mov_b32_e32 v52, v0
	v_mov_b32_e32 v53, v0
	v_mov_b32_e32 v54, v0
	v_mov_b32_e32 v55, v0
	v_mov_b32_e32 v8, v0
	v_mov_b32_e32 v9, v0
	v_mov_b32_e32 v10, v0
	v_mov_b32_e32 v11, v0
	v_mov_b32_e32 v16, v0
	v_mov_b32_e32 v17, v0
	v_mov_b32_e32 v18, v0
	v_mov_b32_e32 v19, v0
	v_mov_b32_e32 v24, v0
	v_mov_b32_e32 v25, v0
	v_mov_b32_e32 v26, v0
	v_mov_b32_e32 v27, v0
	v_mov_b32_e32 v32, v0
	v_mov_b32_e32 v33, v0
	v_mov_b32_e32 v34, v0
	v_mov_b32_e32 v35, v0
	v_mov_b32_e32 v40, v0
	v_mov_b32_e32 v41, v0
	v_mov_b32_e32 v42, v0
	v_mov_b32_e32 v43, v0
	v_mov_b32_e32 v48, v0
	v_mov_b32_e32 v49, v0
	v_mov_b32_e32 v50, v0
	v_mov_b32_e32 v51, v0
	v_mov_b32_e32 v56, v0
	v_mov_b32_e32 v57, v0
	v_mov_b32_e32 v58, v0
	v_mov_b32_e32 v59, v0
	v_mov_b32_e32 v60, v0
	v_mov_b32_e32 v61, v0
	v_mov_b32_e32 v62, v0
	v_mov_b32_e32 v63, v0
	v_mov_b32_e32 v64, v0
	v_mov_b32_e32 v65, v0
	v_mov_b32_e32 v66, v0
	v_mov_b32_e32 v67, v0
	v_mov_b32_e32 v68, v0
	v_mov_b32_e32 v69, v0
	v_mov_b32_e32 v70, v0
	v_mov_b32_e32 v71, v0
	v_mov_b32_e32 v80, v0
	v_mov_b32_e32 v81, v0
	v_mov_b32_e32 v82, v0
	v_mov_b32_e32 v83, v0
	v_mov_b32_e32 v84, v0
	v_mov_b32_e32 v85, v0
	v_mov_b32_e32 v86, v0
	v_mov_b32_e32 v87, v0
	v_mov_b32_e32 v96, v0
	v_mov_b32_e32 v97, v0
	v_mov_b32_e32 v98, v0
	v_mov_b32_e32 v99, v0
	v_mov_b32_e32 v100, v0
	v_mov_b32_e32 v101, v0
	v_mov_b32_e32 v102, v0
	v_mov_b32_e32 v103, v0
	v_mov_b32_e32 v112, v0
	v_mov_b32_e32 v113, v0
	v_mov_b32_e32 v114, v0
	v_mov_b32_e32 v115, v0
	v_mov_b32_e32 v116, v0
	v_mov_b32_e32 v117, v0
	v_mov_b32_e32 v118, v0
	v_mov_b32_e32 v119, v0
	v_mov_b32_e32 v72, v0
	v_mov_b32_e32 v73, v0
	v_mov_b32_e32 v74, v0
	v_mov_b32_e32 v75, v0
	v_mov_b32_e32 v76, v0
	v_mov_b32_e32 v77, v0
	v_mov_b32_e32 v78, v0
	v_mov_b32_e32 v79, v0
	v_mov_b32_e32 v88, v0
	v_mov_b32_e32 v89, v0
	v_mov_b32_e32 v90, v0
	v_mov_b32_e32 v91, v0
	v_mov_b32_e32 v92, v0
	v_mov_b32_e32 v93, v0
	v_mov_b32_e32 v94, v0
	v_mov_b32_e32 v95, v0
	v_mov_b32_e32 v104, v0
	v_mov_b32_e32 v105, v0
	v_mov_b32_e32 v106, v0
	v_mov_b32_e32 v107, v0
	v_mov_b32_e32 v108, v0
	v_mov_b32_e32 v109, v0
	v_mov_b32_e32 v110, v0
	v_mov_b32_e32 v111, v0
	v_mov_b32_e32 v120, v0
	v_mov_b32_e32 v121, v0
	v_mov_b32_e32 v122, v0
	v_mov_b32_e32 v123, v0
	v_mov_b32_e32 v124, v0
	v_mov_b32_e32 v125, v0
	v_mov_b32_e32 v126, v0
	v_mov_b32_e32 v127, v0
	.p2align 6
